# meta-token split-KV units: waves with no valid query rows skip QK/softmax/PV (staging and barriers kept)
# speedup vs baseline: 1.0120x; 1.0102x over previous
; #define SBAR() __builtin_amdgcn_sched_barrier(0)
; #define SLOAD(i, k0) do { const int sv_ = (k0) * (ldv * 2), sk_ = (k0) * (ldk * 2); sr_[i].vs0 = BLD(rsV, vg0 * 2, sv_); sr_[i].vs1 = BLD(rsV, vg1 * 2, sv_); \
;     _Pragma("unroll") for (int q_ = 0; q_ < KPT; ++q_) sr_[i].ks[q_] = BLD(rsK, kg[q_] * 2, sk_); } while (0)
; #define SWRITE(b, i) do { *(bf16x8*)(V_lds + (b) * SHM_V + vst0) = sr_[i].vs0; *(bf16x8*)(V_lds + (b) * SHM_V + vst1) = sr_[i].vs1; \
;     _Pragma("unroll") for (int q_ = 0; q_ < KPT; ++q_) *(bf16x8*)(K_lds + (b) * SHM_K + kst[q_]) = sr_[i].ks[q_]; } while (0)
;     ...
;       if constexpr (DQK == 64 && ATT_KEARLY) {
;         bf16x8 ka[4], kq[4]; const char* Ks = K_lds + b * SHM_K;
; #pragma unroll
;         for (int d0 = 0; d0 < 4; ++d0) { const int cb = (d0 * 16 + hi * 8) * 2;
;           ka[d0] = *reinterpret_cast<const bf16x8*>(Ks + KSWZ(KP, r32, cb)); kq[d0] = *reinterpret_cast<const bf16x8*>(Ks + KSWZ(KP, 32 + r32, cb)); }
;         SBAR();
;         if constexpr (!(ATT_STAGE_LATE & 1)) { if (j + 1 < nt) { SWRITE(b ^ 1, 0); } if (j + 2 < nt) { SLOAD(0, (j + 2) * KVBLK); } SBAR(); }
;         pA0 = f32x16{}; pA1 = f32x16{};
; #pragma unroll
;         for (int d0 = 0; d0 < 4; ++d0) { pA0 = __builtin_amdgcn_mfma_f32_32x32x16_bf16(ka[d0], qr[d0], pA0, 0, 0, 0); pA1 = __builtin_amdgcn_mfma_f32_32x32x16_bf16(kq[d0], qr[d0], pA1, 0, 0, 0); }
;         SBAR();
;         if constexpr (ATT_STAGE_LATE & 1) { if (j + 1 < nt) { SWRITE(b ^ 1, 0); } if (j + 2 < nt) { SLOAD(0, (j + 2) * KVBLK); } SBAR(); }
;       } else {
;       constexpr bool LATE = (DQK == 128) ? ((ATT_STAGE_LATE & 2) != 0) : ((ATT_STAGE_LATE & 4) != 0);
;       if constexpr (!LATE) { if (j + 1 < nt) { SWRITE(b ^ 1, 0); } if (j + 2 < nt) { SLOAD(0, (j + 2) * KVBLK); } }
;       SBAR(); qkt<DQK>(pA0, pA1, K_lds + b * SHM_K, qr, r32, hi); SBAR();
;       if constexpr (LATE) { if (j + 1 < nt) { SWRITE(b ^ 1, 0); } if (j + 2 < nt) { SLOAD(0, (j + 2) * KVBLK); } SBAR(); }
.LBB0_483:
	s_and_b32 s7, s6, 1
	v_lshl_add_u32 v72, s7, 13, v159
	v_add_u32_e32 v68, v72, v161
	v_add_u32_e32 v73, v72, v162
	s_waitcnt lgkmcnt(0)
	s_barrier
	s_cmp_eq_u32 s96, 16
	s_cbranch_scc0 .Lms_a_c1
	s_cmp_ge_u32 s61, 64
	s_cbranch_scc1 .Lms_a_s1
.Lms_a_c1:
	ds_read_b128 v[64:67], v68
	ds_read_b128 v[68:71], v68 offset:4096
	ds_read_b128 v[128:131], v73
	ds_read_b128 v[132:135], v73 offset:4096
	v_add_u32_e32 v73, v72, v163
	v_add_u32_e32 v72, v72, v164
	ds_read_b128 v[136:139], v73
	ds_read_b128 v[140:143], v73 offset:4096
	ds_read_b128 v[172:175], v72
	ds_read_b128 v[176:179], v72 offset:4096
	s_waitcnt lgkmcnt(7)
	v_mfma_f32_32x32x16_bf16 v[80:95], v[64:67], v[100:103], 0
	s_waitcnt lgkmcnt(6)
	v_mfma_f32_32x32x16_bf16 v[64:79], v[68:71], v[100:103], 0
	s_waitcnt lgkmcnt(5)
	v_mfma_f32_32x32x16_bf16 v[80:95], v[128:131], v[104:107], v[80:95]
	s_waitcnt lgkmcnt(4)
	v_mfma_f32_32x32x16_bf16 v[64:79], v[132:135], v[104:107], v[64:79]
	s_waitcnt lgkmcnt(3)
	v_mfma_f32_32x32x16_bf16 v[80:95], v[136:139], v[108:111], v[80:95]
	s_waitcnt lgkmcnt(2)
	v_mfma_f32_32x32x16_bf16 v[64:79], v[140:143], v[108:111], v[64:79]
	s_waitcnt lgkmcnt(1)
	v_mfma_f32_32x32x16_bf16 v[80:95], v[172:175], v[112:115], v[80:95]
	s_waitcnt lgkmcnt(0)
	v_mfma_f32_32x32x16_bf16 v[64:79], v[176:179], v[112:115], v[64:79]
.Lms_a_s1:
	s_add_i32 s12, s6, 1
	s_cmp_ge_u32 s12, s3
	s_cbranch_scc1 .LBB0_485
	s_xor_b32 s8, s7, 1
	s_lshl_b32 s9, s8, 14
	s_add_i32 s9, s9, 0
	v_add_u32_e32 v128, s9, v149
	v_add_u32_e32 v129, s9, v155
	v_lshl_add_u32 v130, s8, 13, v147
	s_waitcnt vmcnt(2)
	ds_write_b128 v128, v[116:119]
	s_waitcnt vmcnt(1)
	ds_write_b128 v129, v[120:123]
	s_waitcnt vmcnt(0)
	ds_write_b128 v130, v[124:127]

; #define SBAR() __builtin_amdgcn_sched_barrier(0)
; #define RESC(a) do { if constexpr (!FIXM) if (__any((a) < 1.f)) { if (hi == 0) al_l[r32] = (a); asm volatile("s_waitcnt lgkmcnt(0)" ::: "memory"); \
;     _Pragma("unroll") for (int d = 0; d < 4; ++d) _Pragma("unroll") for (int r = 0; r < 16; ++r) o[d][r] *= al_l[crow(r, hi)]; } } while (0)
;     ...
;       const int vb = vb0 + b * SHM_V;
;       if constexpr (DQK != 192) {
;         VF f0, f1; v_issue<0>(f0, vb);
;         partialSM<FIXM>(pA0, pA1, m_reg, mnA, alA, C, thrS, kb0 + j * KVBLK, hi);
;         RESC(alA);
;         finishSM<FIXM>(pA0, pA1, alA, l_reg, pa0, pa1, pa2, pa3, kb0 + j * KVBLK, hi); SBAR();
;         pv_pipe(o, vb, f0, f1, pa0, pa1, pa2, pa3);
.LBB0_487:
	s_cmp_eq_u32 s96, 16
	s_cbranch_scc0 .Lms_a_c2
	s_cmp_ge_u32 s61, 64
	s_cbranch_scc1 .Lms_a_tail

;     ...
;     for (int j = 0; j < nt; ++j) {
;       const int b = j & 1;
;       __syncthreads();
.Lms_a_tail:
	s_add_i32 s2, s2, 64
	s_add_i32 s1, s1, 0xb8000
	s_cmp_eq_u32 s3, s12
	s_cbranch_scc1 .LBB0_616
	s_mov_b32 s6, s12
	s_branch .LBB0_483

; #define SBAR() __builtin_amdgcn_sched_barrier(0)
; #define SLOAD(i, k0) do { const int sv_ = (k0) * (ldv * 2), sk_ = (k0) * (ldk * 2); sr_[i].vs0 = BLD(rsV, vg0 * 2, sv_); sr_[i].vs1 = BLD(rsV, vg1 * 2, sv_); \
;     _Pragma("unroll") for (int q_ = 0; q_ < KPT; ++q_) sr_[i].ks[q_] = BLD(rsK, kg[q_] * 2, sk_); } while (0)
; #define SWRITE(b, i) do { *(bf16x8*)(V_lds + (b) * SHM_V + vst0) = sr_[i].vs0; *(bf16x8*)(V_lds + (b) * SHM_V + vst1) = sr_[i].vs1; \
;     _Pragma("unroll") for (int q_ = 0; q_ < KPT; ++q_) *(bf16x8*)(K_lds + (b) * SHM_K + kst[q_]) = sr_[i].ks[q_]; } while (0)
; template <int DQK>
; __device__ __forceinline__ void qkt(f32x16& p0, f32x16& p1, const char* Ks, const bf16x8* qr, int r32, int hi) {
;   constexpr int KP = DQK * 2;
;   p0 = f32x16{}; p1 = f32x16{};
;   if constexpr (DQK == 64 && ATT_KPRELOAD) {
;     bf16x8 ka[4], kq[4];
; #pragma unroll
;     for (int d0 = 0; d0 < 4; ++d0) { const int cb = (d0 * 16 + hi * 8) * 2;
;       ka[d0] = *reinterpret_cast<const bf16x8*>(Ks + KSWZ(KP, r32, cb)); kq[d0] = *reinterpret_cast<const bf16x8*>(Ks + KSWZ(KP, 32 + r32, cb)); }
;     SBAR();
; #pragma unroll
;     for (int d0 = 0; d0 < 4; ++d0) { p0 = __builtin_amdgcn_mfma_f32_32x32x16_bf16(ka[d0], qr[d0], p0, 0, 0, 0); p1 = __builtin_amdgcn_mfma_f32_32x32x16_bf16(kq[d0], qr[d0], p1, 0, 0, 0); }
;     return;
;   }
; #pragma unroll
;   for (int d0 = 0; d0 < DQK / 16; ++d0) { const int cb = (d0 * 16 + hi * 8) * 2;
;     bf16x8 b0 = *reinterpret_cast<const bf16x8*>(Ks + KSWZ(KP, r32, cb));
;     bf16x8 b1 = *reinterpret_cast<const bf16x8*>(Ks + KSWZ(KP, 32 + r32, cb));
;     p0 = __builtin_amdgcn_mfma_f32_32x32x16_bf16(b0, qr[d0], p0, 0, 0, 0);
;     p1 = __builtin_amdgcn_mfma_f32_32x32x16_bf16(b1, qr[d0], p1, 0, 0, 0); }
;     ...
;       constexpr bool LATE = (DQK == 128) ? ((ATT_STAGE_LATE & 2) != 0) : ((ATT_STAGE_LATE & 4) != 0);
;       if constexpr (!LATE) { if (j + 1 < nt) { SWRITE(b ^ 1, 0); } if (j + 2 < nt) { SLOAD(0, (j + 2) * KVBLK); } }
;       SBAR(); qkt<DQK>(pA0, pA1, K_lds + b * SHM_K, qr, r32, hi); SBAR();
;       if constexpr (LATE) { if (j + 1 < nt) { SWRITE(b ^ 1, 0); } if (j + 2 < nt) { SLOAD(0, (j + 2) * KVBLK); } SBAR(); }
.LBB0_660:
	s_waitcnt lgkmcnt(0)
	s_barrier
	s_and_b32 s0, s2, 0x4000
	s_cmp_eq_u32 s96, 16
	s_cbranch_scc0 .Lms_b_c1
	s_cmp_ge_u32 s61, 64
	s_cbranch_scc1 .Lms_b_s1
.Lms_b_c1:
	s_add_i32 s8, s0, 0
	s_add_i32 s8, s8, 0x10000
	v_add3_u32 v68, s8, v217, v216
	ds_read_b128 v[64:67], v68
	v_add3_u32 v152, s8, v218, v216
	ds_read_b128 v[148:151], v152
	s_waitcnt vmcnt(11) lgkmcnt(1)
	v_mfma_f32_32x32x16_bf16 v[80:95], v[64:67], v[100:103], 0
	ds_read_b128 v[64:67], v68 offset:8192
	s_waitcnt vmcnt(10) lgkmcnt(1)
	v_mfma_f32_32x32x16_bf16 v[80:95], v[148:151], v[104:107], v[80:95]
	ds_read_b128 v[148:151], v152 offset:8192
	v_add3_u32 v152, s8, v219, v216
	s_waitcnt lgkmcnt(1)
	v_mfma_f32_32x32x16_bf16 v[64:79], v[64:67], v[100:103], 0
	s_waitcnt lgkmcnt(0)
	v_mfma_f32_32x32x16_bf16 v[64:79], v[148:151], v[104:107], v[64:79]
	ds_read_b128 v[148:151], v152
	s_waitcnt vmcnt(9) lgkmcnt(0)
	v_mfma_f32_32x32x16_bf16 v[80:95], v[148:151], v[108:111], v[80:95]
	ds_read_b128 v[148:151], v152 offset:8192
	v_add3_u32 v152, s8, v220, v216
	s_waitcnt lgkmcnt(0)
	v_mfma_f32_32x32x16_bf16 v[64:79], v[148:151], v[108:111], v[64:79]
	ds_read_b128 v[148:151], v152
	s_waitcnt vmcnt(8) lgkmcnt(0)
	v_mfma_f32_32x32x16_bf16 v[80:95], v[148:151], v[112:115], v[80:95]
	ds_read_b128 v[148:151], v152 offset:8192
	v_add3_u32 v152, s8, v221, v216
	s_waitcnt lgkmcnt(0)
	v_mfma_f32_32x32x16_bf16 v[64:79], v[148:151], v[112:115], v[64:79]
	ds_read_b128 v[148:151], v152
	s_waitcnt vmcnt(7) lgkmcnt(0)
	v_mfma_f32_32x32x16_bf16 v[80:95], v[148:151], v[116:119], v[80:95]
	ds_read_b128 v[148:151], v152 offset:8192
	v_add3_u32 v152, s8, v222, v216
	s_waitcnt lgkmcnt(0)
	v_mfma_f32_32x32x16_bf16 v[64:79], v[148:151], v[116:119], v[64:79]
	ds_read_b128 v[148:151], v152
	s_waitcnt vmcnt(6) lgkmcnt(0)
	v_mfma_f32_32x32x16_bf16 v[80:95], v[148:151], v[120:123], v[80:95]
	ds_read_b128 v[148:151], v152 offset:8192
	v_add3_u32 v152, s8, v223, v216
	s_waitcnt lgkmcnt(0)
	v_mfma_f32_32x32x16_bf16 v[64:79], v[148:151], v[120:123], v[64:79]
	ds_read_b128 v[148:151], v152
	s_waitcnt vmcnt(5) lgkmcnt(0)
	v_mfma_f32_32x32x16_bf16 v[80:95], v[148:151], v[124:127], v[80:95]
	ds_read_b128 v[148:151], v152 offset:8192
	v_add3_u32 v152, s8, v224, v216
	s_waitcnt lgkmcnt(0)
	v_mfma_f32_32x32x16_bf16 v[64:79], v[148:151], v[124:127], v[64:79]
	ds_read_b128 v[148:151], v152
	s_waitcnt vmcnt(4) lgkmcnt(0)
	v_mfma_f32_32x32x16_bf16 v[80:95], v[148:151], v[128:131], v[80:95]
	ds_read_b128 v[148:151], v152 offset:8192
	s_waitcnt lgkmcnt(0)
	v_mfma_f32_32x32x16_bf16 v[64:79], v[148:151], v[128:131], v[64:79]
.Lms_b_s1:
	s_add_i32 s19, s1, 1
	s_cmp_ge_u32 s19, s3
	s_cbranch_scc1 .LBB0_662
	s_xor_b32 s8, s0, 0x4000
	s_add_i32 s8, s8, 0
	v_add_u32_e32 v148, s8, v214
	v_add_u32_e32 v149, s8, v215
	s_add_i32 s8, s8, 0x10000
	v_add_u32_e32 v150, s8, v195
	v_add_u32_e32 v151, s8, v213
	s_waitcnt vmcnt(3)
	ds_write_b128 v148, v[132:135]
	s_waitcnt vmcnt(2)
	ds_write_b128 v149, v[136:139]
	s_waitcnt vmcnt(1)
	ds_write_b128 v150, v[140:143]
	s_waitcnt vmcnt(0)
	ds_write_b128 v151, v[144:147]

;     ...
;     for (int j = 0; j < nt; ++j) {
;       const int b = j & 1;
;       __syncthreads();
.Lms_b_tail:
	s_add_i32 s18, s18, 64
	s_add_i32 s12, s12, 0xb8000
	s_addk_i32 s2, 0x4000
	s_cmp_eq_u32 s3, s19
	s_cbranch_scc1 .LBB0_674
	s_mov_b32 s1, s19
	s_branch .LBB0_660

; #define SBAR() __builtin_amdgcn_sched_barrier(0)
; #define SLOAD(i, k0) do { const int sv_ = (k0) * (ldv * 2), sk_ = (k0) * (ldk * 2); sr_[i].vs0 = BLD(rsV, vg0 * 2, sv_); sr_[i].vs1 = BLD(rsV, vg1 * 2, sv_); \
;     _Pragma("unroll") for (int q_ = 0; q_ < KPT; ++q_) sr_[i].ks[q_] = BLD(rsK, kg[q_] * 2, sk_); } while (0)
; #define SWRITE(b, i) do { *(bf16x8*)(V_lds + (b) * SHM_V + vst0) = sr_[i].vs0; *(bf16x8*)(V_lds + (b) * SHM_V + vst1) = sr_[i].vs1; \
;     _Pragma("unroll") for (int q_ = 0; q_ < KPT; ++q_) *(bf16x8*)(K_lds + (b) * SHM_K + kst[q_]) = sr_[i].ks[q_]; } while (0)
; template <int DQK>
; __device__ __forceinline__ void qkt(f32x16& p0, f32x16& p1, const char* Ks, const bf16x8* qr, int r32, int hi) {
;   constexpr int KP = DQK * 2;
;   p0 = f32x16{}; p1 = f32x16{};
;   if constexpr (DQK == 64 && ATT_KPRELOAD) {
;     bf16x8 ka[4], kq[4];
; #pragma unroll
;     for (int d0 = 0; d0 < 4; ++d0) { const int cb = (d0 * 16 + hi * 8) * 2;
;       ka[d0] = *reinterpret_cast<const bf16x8*>(Ks + KSWZ(KP, r32, cb)); kq[d0] = *reinterpret_cast<const bf16x8*>(Ks + KSWZ(KP, 32 + r32, cb)); }
;     SBAR();
; #pragma unroll
;     for (int d0 = 0; d0 < 4; ++d0) { p0 = __builtin_amdgcn_mfma_f32_32x32x16_bf16(ka[d0], qr[d0], p0, 0, 0, 0); p1 = __builtin_amdgcn_mfma_f32_32x32x16_bf16(kq[d0], qr[d0], p1, 0, 0, 0); }
;     return;
;   }
; #pragma unroll
;   for (int d0 = 0; d0 < DQK / 16; ++d0) { const int cb = (d0 * 16 + hi * 8) * 2;
;     bf16x8 b0 = *reinterpret_cast<const bf16x8*>(Ks + KSWZ(KP, r32, cb));
;     bf16x8 b1 = *reinterpret_cast<const bf16x8*>(Ks + KSWZ(KP, 32 + r32, cb));
;     p0 = __builtin_amdgcn_mfma_f32_32x32x16_bf16(b0, qr[d0], p0, 0, 0, 0);
;     p1 = __builtin_amdgcn_mfma_f32_32x32x16_bf16(b1, qr[d0], p1, 0, 0, 0); }
;     ...
;       constexpr bool LATE = (DQK == 128) ? ((ATT_STAGE_LATE & 2) != 0) : ((ATT_STAGE_LATE & 4) != 0);
;       if constexpr (!LATE) { if (j + 1 < nt) { SWRITE(b ^ 1, 0); } if (j + 2 < nt) { SLOAD(0, (j + 2) * KVBLK); } }
;       SBAR(); qkt<DQK>(pA0, pA1, K_lds + b * SHM_K, qr, r32, hi); SBAR();
;       if constexpr (LATE) { if (j + 1 < nt) { SWRITE(b ^ 1, 0); } if (j + 2 < nt) { SLOAD(0, (j + 2) * KVBLK); } SBAR(); }
.LBB0_718:
	s_and_b32 s12, s0, 1
	s_waitcnt lgkmcnt(0)
	s_barrier
	s_cmp_eq_u32 s96, 16
	s_cbranch_scc0 .Lms_c_c1
	s_cmp_ge_u32 s61, 64
	s_cbranch_scc1 .Lms_c_s1
.Lms_c_c1:
	s_mul_i32 s1, s12, 0x6000
	s_add_i32 s1, s1, 0
	s_add_i32 s1, s1, 0x10000
	v_add3_u32 v68, s1, v223, v222
	ds_read_b128 v[64:67], v68
	v_add3_u32 v172, s1, v224, v222
	ds_read_b128 v[238:241], v172
	s_waitcnt lgkmcnt(1)
	v_mfma_f32_32x32x16_bf16 v[80:95], v[64:67], v[100:103], 0
	ds_read_b128 v[64:67], v68 offset:12288
	s_waitcnt lgkmcnt(1)
	v_mfma_f32_32x32x16_bf16 v[80:95], v[238:241], v[104:107], v[80:95]
	ds_read_b128 v[238:241], v172 offset:12288
	v_add3_u32 v172, s1, v225, v222
	s_waitcnt lgkmcnt(1)
	v_mfma_f32_32x32x16_bf16 v[64:79], v[64:67], v[100:103], 0
	s_waitcnt lgkmcnt(0)
	v_mfma_f32_32x32x16_bf16 v[64:79], v[238:241], v[104:107], v[64:79]
	ds_read_b128 v[238:241], v172
	s_waitcnt lgkmcnt(0)
	v_mfma_f32_32x32x16_bf16 v[80:95], v[238:241], v[108:111], v[80:95]
	ds_read_b128 v[238:241], v172 offset:12288
	v_add3_u32 v172, s1, v226, v222
	s_waitcnt lgkmcnt(0)
	v_mfma_f32_32x32x16_bf16 v[64:79], v[238:241], v[108:111], v[64:79]
	ds_read_b128 v[238:241], v172
	s_waitcnt lgkmcnt(0)
	v_mfma_f32_32x32x16_bf16 v[80:95], v[238:241], v[112:115], v[80:95]
	ds_read_b128 v[238:241], v172 offset:12288
	v_add3_u32 v172, s1, v227, v222
	s_waitcnt lgkmcnt(0)
	v_mfma_f32_32x32x16_bf16 v[64:79], v[238:241], v[112:115], v[64:79]
	ds_read_b128 v[238:241], v172
	s_waitcnt lgkmcnt(0)
	v_mfma_f32_32x32x16_bf16 v[80:95], v[238:241], v[116:119], v[80:95]
	ds_read_b128 v[238:241], v172 offset:12288
	v_add3_u32 v172, s1, v228, v222
	s_waitcnt lgkmcnt(0)
	v_mfma_f32_32x32x16_bf16 v[64:79], v[238:241], v[116:119], v[64:79]
	ds_read_b128 v[238:241], v172
	s_waitcnt lgkmcnt(0)
	v_mfma_f32_32x32x16_bf16 v[80:95], v[238:241], v[120:123], v[80:95]
	ds_read_b128 v[238:241], v172 offset:12288
	v_add3_u32 v172, s1, v229, v222
	s_waitcnt lgkmcnt(0)
	v_mfma_f32_32x32x16_bf16 v[64:79], v[238:241], v[120:123], v[64:79]
	ds_read_b128 v[238:241], v172
	s_waitcnt lgkmcnt(0)
	v_mfma_f32_32x32x16_bf16 v[80:95], v[238:241], v[124:127], v[80:95]
	ds_read_b128 v[238:241], v172 offset:12288
	v_add3_u32 v172, s1, v230, v222
	s_waitcnt lgkmcnt(0)
	v_mfma_f32_32x32x16_bf16 v[64:79], v[238:241], v[124:127], v[64:79]
	ds_read_b128 v[238:241], v172
	s_waitcnt lgkmcnt(0)
	v_mfma_f32_32x32x16_bf16 v[80:95], v[238:241], v[128:131], v[80:95]
	ds_read_b128 v[238:241], v172 offset:12288
	v_add3_u32 v172, s1, v231, v222
	s_waitcnt lgkmcnt(0)
	v_mfma_f32_32x32x16_bf16 v[64:79], v[238:241], v[128:131], v[64:79]
	ds_read_b128 v[238:241], v172
	s_waitcnt lgkmcnt(0)
	v_mfma_f32_32x32x16_bf16 v[80:95], v[238:241], v[132:135], v[80:95]
	ds_read_b128 v[238:241], v172 offset:12288
	v_add3_u32 v172, s1, v232, v222
	s_waitcnt lgkmcnt(0)
	v_mfma_f32_32x32x16_bf16 v[64:79], v[238:241], v[132:135], v[64:79]
	ds_read_b128 v[238:241], v172
	s_waitcnt lgkmcnt(0)
	v_mfma_f32_32x32x16_bf16 v[80:95], v[238:241], v[136:139], v[80:95]
	ds_read_b128 v[238:241], v172 offset:12288
	v_add3_u32 v172, s1, v233, v222
	s_waitcnt lgkmcnt(0)
	v_mfma_f32_32x32x16_bf16 v[64:79], v[238:241], v[136:139], v[64:79]
	ds_read_b128 v[238:241], v172
	s_waitcnt lgkmcnt(0)
	v_mfma_f32_32x32x16_bf16 v[80:95], v[238:241], v[140:143], v[80:95]
	ds_read_b128 v[238:241], v172 offset:12288
	v_add3_u32 v172, s1, v234, v222
	s_waitcnt lgkmcnt(0)
	v_mfma_f32_32x32x16_bf16 v[64:79], v[238:241], v[140:143], v[64:79]
	ds_read_b128 v[238:241], v172
	s_waitcnt lgkmcnt(0)
	v_mfma_f32_32x32x16_bf16 v[80:95], v[238:241], v[144:147], v[80:95]
	ds_read_b128 v[238:241], v172 offset:12288
	s_waitcnt lgkmcnt(0)
	v_mfma_f32_32x32x16_bf16 v[64:79], v[238:241], v[144:147], v[64:79]
.Lms_c_s1:
	s_add_i32 s2, s0, 1
	s_cmp_ge_u32 s2, s3
	s_cbranch_scc1 .LBB0_720
	s_xor_b32 s1, s12, 1
	s_lshl_b32 s6, s1, 14
	s_add_i32 s6, s6, 0
	s_mulk_i32 s1, 0x6000
	v_add_u32_e32 v172, s6, v189
	s_add_i32 s1, s1, 0
	s_waitcnt vmcnt(4)
	ds_write_b128 v172, v[148:151]
	v_add_u32_e32 v172, s6, v191
	s_add_i32 s1, s1, 0x10000
	s_waitcnt vmcnt(3)
	ds_write_b128 v172, v[152:155]
	v_add_u32_e32 v172, s1, v195
	s_waitcnt vmcnt(2)
	ds_write_b128 v172, v[156:159]
	v_add_u32_e32 v172, s1, v218
	s_waitcnt vmcnt(1)
	ds_write_b128 v172, v[160:163]
	v_add_u32_e32 v172, s1, v219
	s_waitcnt vmcnt(0)
	ds_write_b128 v172, v[164:167]

;     ...
;     for (int j = 0; j < nt; ++j) {
;       const int b = j & 1;
;       __syncthreads();
.Lms_c_tail:
	s_add_i32 s34, s34, 64
	s_add_i32 s21, s21, 0x20000
	s_add_i32 s35, s35, 0x18000
	s_cmp_eq_u32 s3, s2
	s_cbranch_scc1 .LBB0_732
	s_mov_b32 s0, s2
	s_branch .LBB0_718
